# v19 + accumulators cleared once per GEMM unit (was twice back to back), with 64 v_mov_b64
# speedup vs baseline: 1.0186x; 1.0072x over previous
; #define PG8_BAR __builtin_amdgcn_s_barrier()
; template <class Epi, class Sched, bool ALIGN_EPI = false, bool SP2 = false, bool F16 = false>
; __device__ __forceinline__ void gemm_phase(PG8_LAS unsigned char* lds, const Gemm g, const Sched& S, const Epi& E) {
;     ...
;         if constexpr (ALIGN_EPI) { if (wr == 0) PG8_BAR; }
;         if constexpr (!Epi::AFTER_DRAIN) { E(acc, cur, wr, wc, fr, fq); S.done(cur); }
;         if (!has_next) break;
; #pragma unroll
;         for (int a = 0; a < 2; ++a)
; #pragma unroll
;             for (int b = 0; b < 2; ++b)
; #pragma unroll
;                 for (int m = 0; m < 4; ++m)
; #pragma unroll
;                     for (int n = 0; n < 2; ++n) acc[a][b][m][n] = (f32x4){0.f, 0.f, 0.f, 0.f};
;         cur = nxt; cA = nA; cB = nB; ++ui;
;         if constexpr (ALIGN_EPI) { if (wr == 1) PG8_BAR; }
.LBB0_308:
	s_andn2_b64 vcc, exec, s[4:5]
	s_waitcnt vmcnt(0)
	v_mov_b64_e32 v[2:3], 0
	v_mov_b64_e32 v[4:5], 0
	v_mov_b64_e32 v[6:7], 0
	v_mov_b64_e32 v[8:9], 0
	v_mov_b64_e32 v[10:11], 0
	v_mov_b64_e32 v[12:13], 0
	v_mov_b64_e32 v[14:15], 0
	v_mov_b64_e32 v[16:17], 0
	v_mov_b64_e32 v[18:19], 0
	v_mov_b64_e32 v[20:21], 0
	v_mov_b64_e32 v[22:23], 0
	v_mov_b64_e32 v[24:25], 0
	v_mov_b64_e32 v[26:27], 0
	v_mov_b64_e32 v[28:29], 0
	v_mov_b64_e32 v[30:31], 0
	v_mov_b64_e32 v[32:33], 0
	v_mov_b64_e32 v[34:35], 0
	v_mov_b64_e32 v[36:37], 0
	v_mov_b64_e32 v[38:39], 0
	v_mov_b64_e32 v[40:41], 0
	v_mov_b64_e32 v[42:43], 0
	v_mov_b64_e32 v[44:45], 0
	v_mov_b64_e32 v[46:47], 0
	v_mov_b64_e32 v[48:49], 0
	v_mov_b64_e32 v[50:51], 0
	v_mov_b64_e32 v[52:53], 0
	v_mov_b64_e32 v[54:55], 0
	v_mov_b64_e32 v[56:57], 0
	v_mov_b64_e32 v[58:59], 0
	v_mov_b64_e32 v[60:61], 0
	v_mov_b64_e32 v[62:63], 0
	v_mov_b64_e32 v[64:65], 0
	v_mov_b64_e32 v[66:67], 0
	v_mov_b64_e32 v[68:69], 0
	v_mov_b64_e32 v[70:71], 0
	v_mov_b64_e32 v[72:73], 0
	v_mov_b64_e32 v[74:75], 0
	v_mov_b64_e32 v[76:77], 0
	v_mov_b64_e32 v[78:79], 0
	v_mov_b64_e32 v[80:81], 0
	v_mov_b64_e32 v[82:83], 0
	v_mov_b64_e32 v[84:85], 0
	v_mov_b64_e32 v[86:87], 0
	v_mov_b64_e32 v[88:89], 0
	v_mov_b64_e32 v[90:91], 0
	v_mov_b64_e32 v[92:93], 0
	v_mov_b64_e32 v[94:95], 0
	v_mov_b64_e32 v[96:97], 0
	v_mov_b64_e32 v[98:99], 0
	v_mov_b64_e32 v[100:101], 0
	v_mov_b64_e32 v[102:103], 0
	v_mov_b64_e32 v[104:105], 0
	v_mov_b64_e32 v[106:107], 0
	v_mov_b64_e32 v[108:109], 0
	v_mov_b64_e32 v[110:111], 0
	v_mov_b64_e32 v[112:113], 0
	v_mov_b64_e32 v[114:115], 0
	v_mov_b64_e32 v[116:117], 0
	v_mov_b64_e32 v[118:119], 0
	v_mov_b64_e32 v[120:121], 0
	v_mov_b64_e32 v[122:123], 0
	v_mov_b64_e32 v[124:125], 0
	v_mov_b64_e32 v[126:127], 0
	v_mov_b64_e32 v[128:129], 0
	s_cbranch_vccnz .LBB0_311
	s_add_u32 s52, s52, 0x80
	s_addc_u32 s53, s53, 0
	s_add_u32 s80, s54, 0x100
	s_addc_u32 s81, s55, 0
	s_mov_b32 s54, 0

; #define PG8_BAR __builtin_amdgcn_s_barrier()
; template <class Epi, class Sched, bool ALIGN_EPI = false, bool SP2 = false, bool F16 = false>
; __device__ __forceinline__ void gemm_phase(PG8_LAS unsigned char* lds, const Gemm g, const Sched& S, const Epi& E) {
;     ...
;         if constexpr (ALIGN_EPI) { if (wr == 0) PG8_BAR; }
;         if constexpr (!Epi::AFTER_DRAIN) { E(acc, cur, wr, wc, fr, fq); S.done(cur); }
;         if (!has_next) break;
; #pragma unroll
;         for (int a = 0; a < 2; ++a)
; #pragma unroll
;             for (int b = 0; b < 2; ++b)
; #pragma unroll
;                 for (int m = 0; m < 4; ++m)
; #pragma unroll
;                     for (int n = 0; n < 2; ++n) acc[a][b][m][n] = (f32x4){0.f, 0.f, 0.f, 0.f};
;         cur = nxt; cA = nA; cB = nB; ++ui;
;         if constexpr (ALIGN_EPI) { if (wr == 1) PG8_BAR; }
.LBB0_343:
	s_andn2_b64 vcc, exec, s[4:5]
	s_waitcnt vmcnt(0)
	v_mov_b64_e32 v[2:3], 0
	v_mov_b64_e32 v[4:5], 0
	v_mov_b64_e32 v[6:7], 0
	v_mov_b64_e32 v[8:9], 0
	v_mov_b64_e32 v[10:11], 0
	v_mov_b64_e32 v[12:13], 0
	v_mov_b64_e32 v[14:15], 0
	v_mov_b64_e32 v[16:17], 0
	v_mov_b64_e32 v[18:19], 0
	v_mov_b64_e32 v[20:21], 0
	v_mov_b64_e32 v[22:23], 0
	v_mov_b64_e32 v[24:25], 0
	v_mov_b64_e32 v[26:27], 0
	v_mov_b64_e32 v[28:29], 0
	v_mov_b64_e32 v[30:31], 0
	v_mov_b64_e32 v[32:33], 0
	v_mov_b64_e32 v[34:35], 0
	v_mov_b64_e32 v[36:37], 0
	v_mov_b64_e32 v[38:39], 0
	v_mov_b64_e32 v[40:41], 0
	v_mov_b64_e32 v[42:43], 0
	v_mov_b64_e32 v[44:45], 0
	v_mov_b64_e32 v[46:47], 0
	v_mov_b64_e32 v[48:49], 0
	v_mov_b64_e32 v[50:51], 0
	v_mov_b64_e32 v[52:53], 0
	v_mov_b64_e32 v[54:55], 0
	v_mov_b64_e32 v[56:57], 0
	v_mov_b64_e32 v[58:59], 0
	v_mov_b64_e32 v[60:61], 0
	v_mov_b64_e32 v[62:63], 0
	v_mov_b64_e32 v[64:65], 0
	v_mov_b64_e32 v[66:67], 0
	v_mov_b64_e32 v[68:69], 0
	v_mov_b64_e32 v[70:71], 0
	v_mov_b64_e32 v[72:73], 0
	v_mov_b64_e32 v[74:75], 0
	v_mov_b64_e32 v[76:77], 0
	v_mov_b64_e32 v[78:79], 0
	v_mov_b64_e32 v[80:81], 0
	v_mov_b64_e32 v[82:83], 0
	v_mov_b64_e32 v[84:85], 0
	v_mov_b64_e32 v[86:87], 0
	v_mov_b64_e32 v[88:89], 0
	v_mov_b64_e32 v[90:91], 0
	v_mov_b64_e32 v[92:93], 0
	v_mov_b64_e32 v[94:95], 0
	v_mov_b64_e32 v[96:97], 0
	v_mov_b64_e32 v[98:99], 0
	v_mov_b64_e32 v[100:101], 0
	v_mov_b64_e32 v[102:103], 0
	v_mov_b64_e32 v[104:105], 0
	v_mov_b64_e32 v[106:107], 0
	v_mov_b64_e32 v[108:109], 0
	v_mov_b64_e32 v[110:111], 0
	v_mov_b64_e32 v[112:113], 0
	v_mov_b64_e32 v[114:115], 0
	v_mov_b64_e32 v[116:117], 0
	v_mov_b64_e32 v[118:119], 0
	v_mov_b64_e32 v[120:121], 0
	v_mov_b64_e32 v[122:123], 0
	v_mov_b64_e32 v[124:125], 0
	v_mov_b64_e32 v[126:127], 0
	v_mov_b64_e32 v[128:129], 0
	s_cbranch_vccnz .LBB0_346
	s_add_u32 s52, s52, 0x80
	s_addc_u32 s53, s53, 0
	s_add_u32 s79, s54, 0x100
	s_addc_u32 s80, s55, 0
	s_mov_b32 s54, 0

; #define PG8_BAR __builtin_amdgcn_s_barrier()
; template <class Epi, class Sched, bool ALIGN_EPI = false, bool SP2 = false, bool F16 = false>
; __device__ __forceinline__ void gemm_phase(PG8_LAS unsigned char* lds, const Gemm g, const Sched& S, const Epi& E) {
;     ...
;         if constexpr (ALIGN_EPI) { if (wr == 0) PG8_BAR; }
;         if constexpr (!Epi::AFTER_DRAIN) { E(acc, cur, wr, wc, fr, fq); S.done(cur); }
;         if (!has_next) break;
; #pragma unroll
;         for (int a = 0; a < 2; ++a)
; #pragma unroll
;             for (int b = 0; b < 2; ++b)
; #pragma unroll
;                 for (int m = 0; m < 4; ++m)
; #pragma unroll
;                     for (int n = 0; n < 2; ++n) acc[a][b][m][n] = (f32x4){0.f, 0.f, 0.f, 0.f};
;         cur = nxt; cA = nA; cB = nB; ++ui;
;         if constexpr (ALIGN_EPI) { if (wr == 1) PG8_BAR; }
.LBB0_396:
	s_andn2_b64 vcc, exec, s[4:5]
	s_waitcnt vmcnt(0)
	v_mov_b64_e32 v[2:3], 0
	v_mov_b64_e32 v[4:5], 0
	v_mov_b64_e32 v[6:7], 0
	v_mov_b64_e32 v[8:9], 0
	v_mov_b64_e32 v[10:11], 0
	v_mov_b64_e32 v[12:13], 0
	v_mov_b64_e32 v[14:15], 0
	v_mov_b64_e32 v[16:17], 0
	v_mov_b64_e32 v[18:19], 0
	v_mov_b64_e32 v[20:21], 0
	v_mov_b64_e32 v[22:23], 0
	v_mov_b64_e32 v[24:25], 0
	v_mov_b64_e32 v[26:27], 0
	v_mov_b64_e32 v[28:29], 0
	v_mov_b64_e32 v[30:31], 0
	v_mov_b64_e32 v[32:33], 0
	v_mov_b64_e32 v[34:35], 0
	v_mov_b64_e32 v[36:37], 0
	v_mov_b64_e32 v[38:39], 0
	v_mov_b64_e32 v[40:41], 0
	v_mov_b64_e32 v[42:43], 0
	v_mov_b64_e32 v[44:45], 0
	v_mov_b64_e32 v[46:47], 0
	v_mov_b64_e32 v[48:49], 0
	v_mov_b64_e32 v[50:51], 0
	v_mov_b64_e32 v[52:53], 0
	v_mov_b64_e32 v[54:55], 0
	v_mov_b64_e32 v[56:57], 0
	v_mov_b64_e32 v[58:59], 0
	v_mov_b64_e32 v[60:61], 0
	v_mov_b64_e32 v[62:63], 0
	v_mov_b64_e32 v[64:65], 0
	v_mov_b64_e32 v[66:67], 0
	v_mov_b64_e32 v[68:69], 0
	v_mov_b64_e32 v[70:71], 0
	v_mov_b64_e32 v[72:73], 0
	v_mov_b64_e32 v[74:75], 0
	v_mov_b64_e32 v[76:77], 0
	v_mov_b64_e32 v[78:79], 0
	v_mov_b64_e32 v[80:81], 0
	v_mov_b64_e32 v[82:83], 0
	v_mov_b64_e32 v[84:85], 0
	v_mov_b64_e32 v[86:87], 0
	v_mov_b64_e32 v[88:89], 0
	v_mov_b64_e32 v[90:91], 0
	v_mov_b64_e32 v[92:93], 0
	v_mov_b64_e32 v[94:95], 0
	v_mov_b64_e32 v[96:97], 0
	v_mov_b64_e32 v[98:99], 0
	v_mov_b64_e32 v[100:101], 0
	v_mov_b64_e32 v[102:103], 0
	v_mov_b64_e32 v[104:105], 0
	v_mov_b64_e32 v[106:107], 0
	v_mov_b64_e32 v[108:109], 0
	v_mov_b64_e32 v[110:111], 0
	v_mov_b64_e32 v[112:113], 0
	v_mov_b64_e32 v[114:115], 0
	v_mov_b64_e32 v[116:117], 0
	v_mov_b64_e32 v[118:119], 0
	v_mov_b64_e32 v[120:121], 0
	v_mov_b64_e32 v[122:123], 0
	v_mov_b64_e32 v[124:125], 0
	v_mov_b64_e32 v[126:127], 0
	v_mov_b64_e32 v[128:129], 0
	s_cbranch_vccnz .LBB0_399
	s_add_u32 s46, s78, 0x80
	s_addc_u32 s47, s79, 0
	s_add_u32 s13, s72, 0x100
	s_addc_u32 s24, s73, 0
	s_mov_b32 s72, 0

; template <class Epi, class Sched, bool ALIGN_EPI = false, bool SP2 = false, bool F16 = false>
; __device__ __forceinline__ void gemm_phase(PG8_LAS unsigned char* lds, const Gemm g, const Sched& S, const Epi& E) {
;     ...
;         const bool has_next = S.next(ui + 1, nxt);
;         const char* nA = has_next ? (const char*)g.A + (size_t)nxt.pm * tstepA : cA; const char* nB = has_next ? (const char*)g.Bt + (size_t)nxt.pn * tstepB : cB;
;         for (int t = 0; t < nt; t += 2) {
;             const bool last = (t == nt - 2);
;             const char* a1 = cA + (size_t)(t + 1) * kstep;
;             const char* a2 = last ? nA : cA + (size_t)(t + 2) * kstep; const char* b2 = last ? nB : cB + (size_t)(t + 2) * kstep;
;             const char* a3 = a2 + kstep; const char* b3 = b2 + kstep;
;     ...
; #pragma unroll
;         for (int a = 0; a < 2; ++a)
; #pragma unroll
;             for (int b = 0; b < 2; ++b)
; #pragma unroll
;                 for (int m = 0; m < 4; ++m)
; #pragma unroll
;                     for (int n = 0; n < 2; ++n) acc[a][b][m][n] = (f32x4){0.f, 0.f, 0.f, 0.f};
.LBB0_562:
	s_andn2_b64 vcc, exec, s[4:5]
	s_waitcnt vmcnt(0)
	v_mov_b64_e32 v[2:3], 0
	v_mov_b64_e32 v[4:5], 0
	v_mov_b64_e32 v[6:7], 0
	v_mov_b64_e32 v[8:9], 0
	v_mov_b64_e32 v[10:11], 0
	v_mov_b64_e32 v[12:13], 0
	v_mov_b64_e32 v[14:15], 0
	v_mov_b64_e32 v[16:17], 0
	v_mov_b64_e32 v[18:19], 0
	v_mov_b64_e32 v[20:21], 0
	v_mov_b64_e32 v[22:23], 0
	v_mov_b64_e32 v[24:25], 0
	v_mov_b64_e32 v[26:27], 0
	v_mov_b64_e32 v[28:29], 0
	v_mov_b64_e32 v[30:31], 0
	v_mov_b64_e32 v[32:33], 0
	v_mov_b64_e32 v[34:35], 0
	v_mov_b64_e32 v[36:37], 0
	v_mov_b64_e32 v[38:39], 0
	v_mov_b64_e32 v[40:41], 0
	v_mov_b64_e32 v[42:43], 0
	v_mov_b64_e32 v[44:45], 0
	v_mov_b64_e32 v[46:47], 0
	v_mov_b64_e32 v[48:49], 0
	v_mov_b64_e32 v[50:51], 0
	v_mov_b64_e32 v[52:53], 0
	v_mov_b64_e32 v[54:55], 0
	v_mov_b64_e32 v[56:57], 0
	v_mov_b64_e32 v[58:59], 0
	v_mov_b64_e32 v[60:61], 0
	v_mov_b64_e32 v[62:63], 0
	v_mov_b64_e32 v[64:65], 0
	v_mov_b64_e32 v[66:67], 0
	v_mov_b64_e32 v[68:69], 0
	v_mov_b64_e32 v[70:71], 0
	v_mov_b64_e32 v[72:73], 0
	v_mov_b64_e32 v[74:75], 0
	v_mov_b64_e32 v[76:77], 0
	v_mov_b64_e32 v[78:79], 0
	v_mov_b64_e32 v[80:81], 0
	v_mov_b64_e32 v[82:83], 0
	v_mov_b64_e32 v[84:85], 0
	v_mov_b64_e32 v[86:87], 0
	v_mov_b64_e32 v[88:89], 0
	v_mov_b64_e32 v[90:91], 0
	v_mov_b64_e32 v[92:93], 0
	v_mov_b64_e32 v[94:95], 0
	v_mov_b64_e32 v[96:97], 0
	v_mov_b64_e32 v[98:99], 0
	v_mov_b64_e32 v[100:101], 0
	v_mov_b64_e32 v[102:103], 0
	v_mov_b64_e32 v[104:105], 0
	v_mov_b64_e32 v[106:107], 0
	v_mov_b64_e32 v[108:109], 0
	v_mov_b64_e32 v[110:111], 0
	v_mov_b64_e32 v[112:113], 0
	v_mov_b64_e32 v[114:115], 0
	v_mov_b64_e32 v[116:117], 0
	v_mov_b64_e32 v[118:119], 0
	v_mov_b64_e32 v[120:121], 0
	v_mov_b64_e32 v[122:123], 0
	v_mov_b64_e32 v[124:125], 0
	v_mov_b64_e32 v[126:127], 0
	v_mov_b64_e32 v[128:129], 0
	s_cbranch_vccnz .LBB0_565
	s_add_u32 s44, s72, 0x80
	s_addc_u32 s45, s73, 0
	s_add_u32 s24, s52, 0x100
	s_addc_u32 s72, s53, 0
	s_mov_b32 s52, 0
